# e56 + out_proj first-tile gate/x preload issued inside the P6->P7 barrier wait (e50)
# baseline (speedup 1.0000x reference)
; __device__ __forceinline__ f32x4 ld_nt(const float* p) { return __builtin_nontemporal_load((const f32x4*)p); }
;     __device__ __forceinline__ void operator()(AccRef acc, const Unit& u, int wr, int wc, int fr, int fq) const {
;         int row0 = u.pm * 256 + wr * 64 + fr; asm volatile("" : "+v"(row0)); int col0 = u.pn * 256 + wc * 32 + 8 * fq; asm volatile("" : "+v"(col0));
;         const float* gate = mod + (size_t)(u.pm >= 32 ? 1 : 0) * 3 * D + 2 * D + col0;
;         f32x4 gv[2][2];
; #pragma unroll
;         for (int bj = 0; bj < 2; ++bj)
; #pragma unroll
;             for (int n = 0; n < 2; ++n) gv[bj][n] = *(const f32x4*)(gate + bj * HALF + n * 4);
; #pragma unroll
;         for (int ai = 0; ai < 2; ++ai)
; #pragma unroll
;             for (int mp = 0; mp < 2; ++mp) { f32x4 xv[2][2][2];
; #pragma unroll
;                 for (int mm = 0; mm < 2; ++mm)
; #pragma unroll
;                     for (int bj = 0; bj < 2; ++bj)
; #pragma unroll
;                         for (int n = 0; n < 2; ++n) xv[mm][bj][n] = ld_nt(x + (size_t)(row0 + ai * HALF + (mp * 2 + mm) * 16) * D + col0 + bj * HALF + n * 4);
.LBB0_1077:
	s_mov_b32 s101, 0
	s_cmp_gt_i32 s79, 7
	s_cselect_b64 s[2:3], -1, 0
	s_and_b64 s[0:1], s[4:5], s[2:3]
	s_andn2_b64 vcc, exec, s[0:1]
	s_cbranch_vccnz .LBB0_1131
	s_waitcnt vmcnt(0)
	s_waitcnt vmcnt(0)
	s_barrier
	v_readfirstlane_b32 s98, v0
	s_lshr_b32 s98, s98, 6
	s_cmp_eq_u32 s98, 0
	s_cbranch_scc1 .Lp7e_skipA
	s_and_b32 vcc_lo, s16, 7
	s_lshl_b32 vcc_lo, vcc_lo, 6
	s_lshr_b32 vcc_hi, s16, 3
	s_add_i32 vcc_lo, vcc_lo, vcc_hi
	s_lshr_b32 vcc_hi, vcc_lo, 3
	s_and_b32 vcc_lo, vcc_lo, 7
	v_and_b32_e32 v252, 15, v0
	v_lshrrev_b32_e32 v253, 8, v0
	v_lshl_or_b32 v252, v253, 6, v252
	v_bfe_u32 v253, v0, 6, 2
	v_bfe_u32 v251, v0, 4, 2
	v_lshlrev_b32_e32 v251, 2, v251
	v_lshl_or_b32 v253, v253, 5, v251
	v_lshl_add_u32 v250, vcc_hi, 8, v252
	v_lshl_or_b32 v251, vcc_lo, 8, v253
	v_readlane_b32 s98, v254, 2
	v_readlane_b32 s99, v254, 3
	v_lshlrev_b32_e32 v250, 13, v250
	v_lshlrev_b32_e32 v251, 2, v251
	s_cmp_gt_i32 vcc_hi, 31
	s_cselect_b32 s100, 0x6000, 0
	s_add_u32 s100, s50, s100
	s_addc_u32 s101, s51, 0
	s_add_u32 s100, s100, 0x104000
	s_addc_u32 s101, s101, 0
	v_add_u32_e32 v250, v250, v251
	s_nop 1
	global_load_dwordx4 v[218:221], v251, s[100:101]
	global_load_dwordx4 v[222:225], v251, s[100:101] offset:64
	global_load_dwordx4 v[226:229], v251, s[100:101] offset:512
	global_load_dwordx4 v[230:233], v251, s[100:101] offset:576
	global_load_dwordx4 v[234:237], v250, s[98:99] nt
	global_load_dwordx4 v[238:241], v250, s[98:99] offset:64 nt
	global_load_dwordx4 v[242:245], v250, s[98:99] offset:512 nt
	global_load_dwordx4 v[246:249], v250, s[98:99] offset:576 nt
	s_movk_i32 s101, 0x1234
.Lp7e_skipA:
	s_and_saveexec_b64 s[4:5], s[82:83]
	s_cbranch_execz .LBB0_1130
	s_add_i32 s0, 0, 0x23000
	v_mov_b32_e32 v1, s0
	s_waitcnt vmcnt(0) expcnt(0) lgkmcnt(0)
	ds_read_b32 v3, v1
	s_add_i32 s0, 0, 0x23004
	v_mov_b32_e32 v1, s0
	ds_read_b32 v1, v1
	s_waitcnt lgkmcnt(1)
	v_cmp_ne_u32_e32 vcc, 0, v3
	s_cbranch_vccnz .LBB0_1094
	v_readlane_b32 s6, v254, 0
	v_readlane_b32 s7, v254, 1
	s_load_dwordx2 s[0:1], s[6:7], 0x4
	s_add_u32 s6, s50, 0x1000
	s_addc_u32 s7, s51, 0
	s_add_u32 s8, s50, 0x1100
	s_addc_u32 s9, s51, 0
	s_add_u32 s10, s50, 0x1200
	s_addc_u32 s11, s51, 0
	s_waitcnt lgkmcnt(0)
	s_mul_i32 s0, s0, s17
	s_add_u32 s12, s50, 0x1300
	s_mul_i32 s0, s0, s1
	s_addc_u32 s13, s51, 0
	s_mov_b32 s1, 1
	v_mov_b32_e32 v17, 0
	s_branch .LBB0_1082

; __device__ __forceinline__ f32x4 ld_nt(const float* p) { return __builtin_nontemporal_load((const f32x4*)p); }
; __device__ __forceinline__ unsigned xb_ld(unsigned* p)              { return __hip_atomic_load(p, __ATOMIC_RELAXED, __HIP_MEMORY_SCOPE_AGENT); }
; __device__ __forceinline__ unsigned xb_add(unsigned* p, unsigned v) { return __hip_atomic_fetch_add(p, v, __ATOMIC_RELAXED, __HIP_MEMORY_SCOPE_AGENT); }
; #define XB_SPIN(cond, bar) do { unsigned _sp = 0; while (cond) { __builtin_amdgcn_s_sleep(1); \
;     if ((++_sp & 255u) == 0u) { if (xb_ld(&(bar)[XB_TMO])) break; if (_sp > XB_SPIN_CAP) { atomicAdd(&(bar)[XB_TMO], 1u); break; } } } } while (0)
;     __device__ __forceinline__ void operator()(AccRef acc, const Unit& u, int wr, int wc, int fr, int fq) const {
;         int row0 = u.pm * 256 + wr * 64 + fr; asm volatile("" : "+v"(row0)); int col0 = u.pn * 256 + wc * 32 + 8 * fq; asm volatile("" : "+v"(col0));
;         const float* gate = mod + (size_t)(u.pm >= 32 ? 1 : 0) * 3 * D + 2 * D + col0;
;         f32x4 gv[2][2];
; #pragma unroll
;         for (int bj = 0; bj < 2; ++bj)
; #pragma unroll
;             for (int n = 0; n < 2; ++n) gv[bj][n] = *(const f32x4*)(gate + bj * HALF + n * 4);
; #pragma unroll
;         for (int ai = 0; ai < 2; ++ai)
; #pragma unroll
;             for (int mp = 0; mp < 2; ++mp) { f32x4 xv[2][2][2];
; #pragma unroll
;                 for (int mm = 0; mm < 2; ++mm)
; #pragma unroll
;                     for (int bj = 0; bj < 2; ++bj)
; #pragma unroll
;                         for (int n = 0; n < 2; ++n) xv[mm][bj][n] = ld_nt(x + (size_t)(row0 + ai * HALF + (mp * 2 + mm) * 16) * D + col0 + bj * HALF + n * 4);
; __device__ __forceinline__ void xcd_barrier(const XcdBarrier& b) {
;     ...
;             const unsigned og = xb_add(&bar[XB_TOP], 1u);
;             const unsigned tg = og / nx;
;             if (og + 1u == (tg + 1u) * nx) xb_add(&bar[XB_TOPGEN], 1u);
;             else XB_SPIN(xb_ld(&bar[XB_TOPGEN]) == tg, bar);
;             __builtin_amdgcn_fence(__ATOMIC_ACQUIRE, "agent");
;             xb_add(&bar[XB_XGEN(b.x)], 1u);
;             asm volatile("s_waitcnt vmcnt(0)" ::: "memory");
;         } else {
;             XB_SPIN(xb_ld(&bar[XB_XGEN(b.x)]) == gen, bar);
.LBB0_1096:
	s_or_b64 exec, exec, s[10:11]
	v_cvt_f32_u32_e32 v5, v3
	s_waitcnt vmcnt(0)
	v_readfirstlane_b32 s0, v4
	v_sub_u32_e32 v4, 0, v3
	v_rcp_iflag_f32_e32 v5, v5
	v_add_u32_e32 v6, s0, v2
	v_mul_f32_e32 v5, 0x4f7ffffe, v5
	v_cvt_u32_f32_e32 v5, v5
	v_mul_lo_u32 v2, v4, v5
	v_mul_hi_u32 v2, v5, v2
	v_add_u32_e32 v2, v5, v2
	v_mul_hi_u32 v2, v6, v2
	v_mul_lo_u32 v4, v2, v3
	v_sub_u32_e32 v4, v6, v4
	v_add_u32_e32 v5, 1, v2
	v_cmp_ge_u32_e32 vcc, v4, v3
	s_nop 1
	v_cndmask_b32_e32 v2, v2, v5, vcc
	v_sub_u32_e32 v5, v4, v3
	v_cndmask_b32_e32 v4, v4, v5, vcc
	v_add_u32_e32 v5, 1, v2
	v_cmp_ge_u32_e32 vcc, v4, v3
	v_add_u32_e32 v4, 1, v6
	s_nop 0
	v_cndmask_b32_e32 v2, v2, v5, vcc
	v_mul_lo_u32 v5, v3, v2
	v_add_u32_e32 v3, v5, v3
	v_cmp_ne_u32_e32 vcc, v4, v3
	s_and_saveexec_b64 s[0:1], vcc
	s_xor_b64 s[8:9], exec, s[0:1]
	s_cbranch_execz .LBB0_1110
	s_mov_b64 s[20:21], exec
	s_mov_b64 exec, -1
	s_and_b32 vcc_lo, s16, 7
	s_lshl_b32 vcc_lo, vcc_lo, 6
	s_lshr_b32 vcc_hi, s16, 3
	s_add_i32 vcc_lo, vcc_lo, vcc_hi
	s_lshr_b32 vcc_hi, vcc_lo, 3
	s_and_b32 vcc_lo, vcc_lo, 7
	v_and_b32_e32 v252, 15, v0
	v_lshrrev_b32_e32 v253, 8, v0
	v_lshl_or_b32 v252, v253, 6, v252
	v_bfe_u32 v253, v0, 6, 2
	v_bfe_u32 v251, v0, 4, 2
	v_lshlrev_b32_e32 v251, 2, v251
	v_lshl_or_b32 v253, v253, 5, v251
	v_lshl_add_u32 v250, vcc_hi, 8, v252
	v_lshl_or_b32 v251, vcc_lo, 8, v253
	v_readlane_b32 s98, v254, 2
	v_readlane_b32 s99, v254, 3
	v_lshlrev_b32_e32 v250, 13, v250
	v_lshlrev_b32_e32 v251, 2, v251
	s_cmp_gt_i32 vcc_hi, 31
	s_cselect_b32 s100, 0x6000, 0
	s_add_u32 s100, s50, s100
	s_addc_u32 s101, s51, 0
	s_add_u32 s100, s100, 0x104000
	s_addc_u32 s101, s101, 0
	v_add_u32_e32 v250, v250, v251
	s_nop 1
	global_load_dwordx4 v[218:221], v251, s[100:101]
	global_load_dwordx4 v[222:225], v251, s[100:101] offset:64
	global_load_dwordx4 v[226:229], v251, s[100:101] offset:512
	global_load_dwordx4 v[230:233], v251, s[100:101] offset:576
	global_load_dwordx4 v[234:237], v250, s[98:99] nt
	global_load_dwordx4 v[238:241], v250, s[98:99] offset:64 nt
	global_load_dwordx4 v[242:245], v250, s[98:99] offset:512 nt
	global_load_dwordx4 v[246:249], v250, s[98:99] offset:576 nt
	s_movk_i32 s101, 0x1234
	s_mov_b64 exec, s[20:21]
	s_waitcnt lgkmcnt(0)
	buffer_inv sc1
	v_mov_b32_e32 v2, 4
	v_mov_b32_e32 v1, 0x3500
	global_load_dword v1, v1, s[50:51] sc1
	s_add_u32 s12, s50, 0x3500
	s_addc_u32 s13, s51, 0
	s_waitcnt vmcnt(0)
	v_cmp_eq_u32_e32 vcc, v1, v2
	s_and_saveexec_b64 s[10:11], vcc
	s_cbranch_execz .LBB0_1109
	s_mov_b32 s0, 1
	s_mov_b64 s[14:15], 0
	v_mov_b32_e32 v1, 0
	s_branch .LBB0_1100

; __device__ __forceinline__ f32x4 ld_nt(const float* p) { return __builtin_nontemporal_load((const f32x4*)p); }
; #define PG8_STAGE_A(bufoff, gbase) PG8_STAGE(bufoff, gbase, voffA, a64)
; #define PG8_STAGE_B(bufoff, bp, hb, tz) do { if (BMODE == 1 && (tz)) PG8_STAGE(bufoff, (bp) + (hb) * 4096, voffT, t64); else PG8_STAGE(bufoff, (bp) + (hb) * bhstep, voffB, b64); } while (0)
; #define PG8_WAIT_V(n) asm volatile("s_waitcnt vmcnt(" #n ")" ::: "memory")
; #define PG8_BAR __builtin_amdgcn_s_barrier()
; template <class CF, class Epi, class Sched, bool ALIGN_EPI, bool SP2>
; __device__ __forceinline__ void gemm_phase(LAS unsigned char* lds, const char* gA, const char* gB, const Sched& S, const Epi& E, const char* gB2 = nullptr) {
;     ...
;     const char* cA = gA + (size_t)cur.g * CF::A_G + (size_t)cur.pm * CF::A_T; const char* cB = gB + (size_t)cur.g * CF::B_G + (size_t)cur.pn * CF::B_T;
;     const char* cT = BMODE == 1 ? gB2 + (size_t)cur.g * KTG + (size_t)cur.pn * 8192 + 14336 : nullptr;
;     PG8_STAGE_B(PG8_SB(0, 0), cB, 0, false); PG8_STAGE_B(PG8_SB(0, 1), cB, 1, false); PG8_STAGE_A(PG8_SA(0, 0), cA); PG8_STAGE_A(PG8_SA(0, 1), cA + ahstep);
;     if (wr == 1) PG8_BAR;
;     PG8_WAIT_V(2); PG8_BAR;
;     PG8_STAGE_B(PG8_SB(1, 0), cB + bkstep, 0, false); PG8_STAGE_A(PG8_SA(1, 0), cA + akstep); PG8_STAGE_B(PG8_SB(1, 1), cB + bkstep, 1, false);
;     PG8_WAIT_V(6); PG8_BAR;
;     __device__ __forceinline__ void operator()(AccRef acc, const Unit& u, int wr, int wc, int fr, int fq) const {
;         int row0 = u.pm * 256 + wr * 64 + fr; asm volatile("" : "+v"(row0)); int col0 = u.pn * 256 + wc * 32 + 8 * fq; asm volatile("" : "+v"(col0));
;         const float* gate = mod + (size_t)(u.pm >= 32 ? 1 : 0) * 3 * D + 2 * D + col0;
;         f32x4 gv[2][2];
; #pragma unroll
;         for (int bj = 0; bj < 2; ++bj)
; #pragma unroll
;             for (int n = 0; n < 2; ++n) gv[bj][n] = *(const f32x4*)(gate + bj * HALF + n * 4);
; #pragma unroll
;         for (int ai = 0; ai < 2; ++ai)
; #pragma unroll
;             for (int mp = 0; mp < 2; ++mp) { f32x4 xv[2][2][2];
; #pragma unroll
;                 for (int mm = 0; mm < 2; ++mm)
; #pragma unroll
;                     for (int bj = 0; bj < 2; ++bj)
; #pragma unroll
;                         for (int n = 0; n < 2; ++n) xv[mm][bj][n] = ld_nt(x + (size_t)(row0 + ai * HALF + (mp * 2 + mm) * 16) * D + col0 + bj * HALF + n * 4);
.LBB0_1138:
	s_andn2_b64 vcc, exec, s[2:3]
	s_cbranch_vccnz .LBB0_1174
	s_cmpk_eq_u32 s101, 0x1234
	s_cbranch_scc1 .Lp7e_done
	v_and_b32_e32 v252, 15, v0
	v_lshrrev_b32_e32 v253, 8, v0
	v_lshl_or_b32 v252, v253, 6, v252
	v_bfe_u32 v253, v0, 6, 2
	v_bfe_u32 v251, v0, 4, 2
	v_lshlrev_b32_e32 v251, 2, v251
	v_lshl_or_b32 v253, v253, 5, v251
	v_lshl_add_u32 v250, s58, 8, v252
	v_lshl_or_b32 v251, s22, 8, v253
	v_readlane_b32 s98, v254, 2
	v_readlane_b32 s99, v254, 3
	v_lshlrev_b32_e32 v250, 13, v250
	v_lshlrev_b32_e32 v251, 2, v251
	s_cmp_gt_i32 s58, 31
	s_cselect_b32 vcc_lo, 0x6000, 0
	s_add_u32 s100, s50, vcc_lo
	s_addc_u32 s101, s51, 0
	s_add_u32 s100, s100, 0x104000
	s_addc_u32 s101, s101, 0
	v_add_u32_e32 v250, v250, v251
	s_nop 1
	global_load_dwordx4 v[218:221], v251, s[100:101]
	global_load_dwordx4 v[222:225], v251, s[100:101] offset:64
	global_load_dwordx4 v[226:229], v251, s[100:101] offset:512
	global_load_dwordx4 v[230:233], v251, s[100:101] offset:576
	global_load_dwordx4 v[234:237], v250, s[98:99] nt
	global_load_dwordx4 v[238:241], v250, s[98:99] offset:64 nt
	global_load_dwordx4 v[242:245], v250, s[98:99] offset:512 nt
	global_load_dwordx4 v[246:249], v250, s[98:99] offset:576 nt
.Lp7e_done:
	s_add_u32 s0, s50, 0x19800000
	s_addc_u32 s1, s51, 0
	s_add_u32 s33, s50, 0x1400000
	s_addc_u32 s64, s51, 0
	s_lshr_b32 s3, s18, 6
	s_ashr_i32 s59, s58, 31
	s_lshr_b32 s2, s18, 8
	s_lshl_b32 s65, s3, 10
	s_lshl_b64 s[4:5], s[58:59], 20
	v_lshlrev_b32_e32 v2, 4, v0
	v_and_b32_e32 v3, 32, v0
	v_lshrrev_b32_e32 v4, 3, v0
	v_bfe_u32 v1, v0, 2, 4
	s_add_u32 s20, s0, s4
	v_and_or_b32 v5, v4, 48, v1
	v_bitop3_b32 v6, v2, v3, 48 bitop3:0x6c
	v_and_b32_e32 v3, 32, v4
	v_lshrrev_b32_e32 v4, 1, v0
	v_lshrrev_b32_e32 v8, 5, v0
	v_bfe_u32 v9, v0, 2, 2
	s_addc_u32 s21, s1, s5
	s_ashr_i32 s23, s22, 31
	v_and_b32_e32 v7, 64, v0
	v_and_b32_e32 v4, 24, v4
	v_and_or_b32 v8, v8, 4, v9
	s_lshl_b64 s[4:5], s[22:23], 20
	v_or_b32_e32 v2, v6, v7
	v_or3_b32 v3, v8, v3, v4
	s_add_u32 s62, s33, s4
	v_lshl_or_b32 v162, v5, 12, v2
	s_addc_u32 s63, s64, s5
	v_mov_b32_e32 v163, 0
	s_add_i32 s66, s65, 0
	v_lshl_or_b32 v160, v5, 12, v2
	v_lshl_add_u64 v[2:3], s[62:63], 0, v[162:163]
	s_add_i32 m0, s66, 0x10000
	s_mov_b64 s[8:9], 0x40000
	global_load_lds_dwordx4 v162, s[62:63]
	v_lshl_add_u64 v[4:5], v[2:3], 0, s[8:9]
	s_add_i32 m0, s66, 0x12000
	s_mov_b64 s[10:11], 0x80000
	global_load_lds_dwordx4 v[4:5], off
	v_lshl_add_u64 v[4:5], v[2:3], 0, s[10:11]
	s_add_i32 m0, s66, 0x14000
	s_mov_b64 s[12:13], 0xc0000
	global_load_lds_dwordx4 v[4:5], off
	v_lshl_add_u64 v[4:5], v[2:3], 0, s[12:13]
	s_add_i32 m0, s66, 0x16000
	v_mov_b32_e32 v161, v163
	global_load_lds_dwordx4 v[4:5], off
	v_lshl_add_u64 v[4:5], s[20:21], 0, v[160:161]
	s_mov_b32 m0, s66
	s_add_i32 s67, s66, 0x2000
	global_load_lds_dwordx4 v160, s[20:21]
	v_lshl_add_u64 v[8:9], v[4:5], 0, s[8:9]
	s_mov_b32 m0, s67
	s_add_i32 s68, s66, 0x4000
	global_load_lds_dwordx4 v[8:9], off
	v_lshl_add_u64 v[8:9], v[4:5], 0, s[10:11]
	s_mov_b32 m0, s68
	s_add_i32 s69, s66, 0x6000
	global_load_lds_dwordx4 v[8:9], off
	v_lshl_add_u64 v[8:9], v[4:5], 0, s[12:13]
	s_mov_b32 m0, s69
	v_writelane_b32 v254, s82, 18
	global_load_lds_dwordx4 v[8:9], off
	s_nop 0
	v_writelane_b32 v254, s83, 19
	s_cmp_eq_u32 s2, 1
	s_mov_b32 s96, s53
	s_mov_b32 s53, s81
	v_writelane_b32 v254, s78, 36
	s_cselect_b64 s[14:15], -1, 0
	s_cmp_lg_u32 s2, 1
	s_mov_b32 s23, 0
	v_writelane_b32 v254, s79, 37
	s_cbranch_scc1 .LBB0_1141
	s_barrier
